# kernel-wide static priority raise for waves 4-7 (set once before the phase loop), GEMM per-phase flips removed
# baseline (speedup 1.0000x reference)
; #define LAS __attribute__((address_space(3)))
; __global__ void __launch_bounds__(512, 2) mega(P p, int ph_lo, int ph_hi, unsigned ph_mask) {
;     extern __shared__ __attribute__((aligned(16))) unsigned char lds_raw[];
;     LAS unsigned char* lds = (LAS unsigned char*)lds_raw;
;     cg::grid_group grid = cg::this_grid();
;     const int G = gridDim.x, c = blockIdx.x;
;     unsigned char* ws = p.ws;
;     volatile LAS unsigned* xbst = (volatile LAS unsigned*)(lds + LDS_BYTES - 16);
;     if (threadIdx.x < 4) xbst[threadIdx.x] = 0u;
;     __syncthreads();
;     const XcdBarrier xbar = xcd_barrier_post((unsigned*)(ws + W_BAR), xbst);
;     if (ph_lo > 1000) grid.sync();
; #pragma unroll 1
;     for (int ph2 = ph_lo * 2; ph2 < ph_hi * 2; ++ph2) {
;         const int ph = ph2 >> 1;
;         if (ph == 9 || ph == 10 || ph == 21 || ph == 22) continue;
;         if (FUSE_RMS_TAIL && (ph == 6 || ph == 12 || ph == 18 || ph == 24)) continue;
;         if ((ph2 & 1) && !((DUP_MASK >> ph) & 1u)) continue;
;         if (ph2 & 1) __syncthreads();
;         int tid = threadIdx.x; asm volatile("" : "+v"(tid));
;         int kind = ph, layer = 0, sub = 0;
;         if (ph >= 6 && ph <= 11) { kind = 100; layer = 0; sub = ph - 6; }
;         if (ph >= 18 && ph <= 23) { kind = 100; layer = 1; sub = ph - 18; }
;         if (kind == 100) kind = (sub == 0) ? 100 : (sub == 5) ? 103 : (sub & 1) ? 101 : 102;
;         const int half = (sub - 1) >> 1;
;         bool gdirect = false; const float* tail_g = nullptr; bf16_t* tail_dst = nullptr; bool tail = false;
;         bool is_gemm = false; const bf16_t* gA = nullptr; const bf16_t* gB = nullptr; int lda = 0, ldb = 0, gM = 0, gN = 0, gK = 0, gG = G, gc = c;
.LBB0_18:
	s_mov_b32 s14, s2
	s_lshl_b32 s2, s2, 6
	s_lshl_b32 s20, s18, 6
	s_add_u32 vcc_lo, s54, 0x22000000
	s_addc_u32 vcc_hi, s55, 0
	v_writelane_b32 v250, s2, 0
	s_add_u32 s2, s54, 0x28e0000
	s_addc_u32 s3, s55, 0
	v_writelane_b32 v250, s2, 1
	s_mov_b32 s6, 0x21c00000
	s_brev_b32 s9, 40
	v_writelane_b32 v250, s3, 2
	s_add_u32 s2, s54, 0xc000000
	s_addc_u32 s3, s55, 0
	v_writelane_b32 v250, s2, 3
	s_mov_b32 s10, 0x10a0000
	s_load_dwordx16 s[72:87], s[0:1], 0xc0
	v_writelane_b32 v250, s3, 4
	s_lshl_b32 s2, s14, 9
	v_writelane_b32 v250, s2, 5
	s_lshl_b32 s2, s18, 9
	v_writelane_b32 v250, s2, 6
	s_add_u32 s2, s54, 0x4000000
	s_addc_u32 s3, s55, 0
	v_writelane_b32 v250, s2, 7
	s_load_dwordx16 s[56:71], s[0:1], 0x80
	s_mov_b32 s13, s11
	v_writelane_b32 v250, s3, 8
	s_add_u32 s2, s54, 0x12e0000
	s_addc_u32 s3, s55, 0
	v_writelane_b32 v250, s2, 9
	s_waitcnt lgkmcnt(0)
	s_mov_b64 s[94:95], s[70:71]
	s_mov_b64 s[92:93], s[68:69]
	v_writelane_b32 v250, s3, 10
	s_add_u32 s2, s54, 0xea0000
	s_addc_u32 s3, s55, 0
	v_writelane_b32 v250, s2, 11
	s_mov_b64 s[90:91], s[66:67]
	v_mov_b32_e32 v181, 0
	v_writelane_b32 v250, s3, 12
	s_add_u32 s2, s54, 0x21c00000
	v_writelane_b32 v250, s2, 13
	s_addc_u32 s2, s55, 0
	v_writelane_b32 v250, s2, 14
	s_add_u32 s2, s54, 0x21e00000
	v_writelane_b32 v250, s2, 15
	s_addc_u32 s2, s55, 0
	v_writelane_b32 v250, s2, 16
	s_add_u32 s2, s54, 0x20000000
	s_addc_u32 s3, s55, 0
	v_writelane_b32 v250, s2, 17
	s_cmpk_lt_i32 s14, 0x1000
	v_mov_b32_e32 v235, 0xf149f2ca
	v_writelane_b32 v250, s3, 18
	s_cselect_b64 s[2:3], -1, 0
	s_lshr_b32 s4, s18, 31
	v_writelane_b32 v250, s2, 19
	s_add_i32 s4, s18, s4
	v_mov_b32_e32 v236, 0xce6e6b28
	v_writelane_b32 v250, s3, 20
	s_ashr_i32 s2, s4, 1
	s_cmp_lt_i32 s14, s2
	s_cselect_b64 s[4:5], -1, 0
	v_writelane_b32 v250, s4, 21
	v_mov_b32_e32 v237, 0x7f800000
	v_not_b32_e32 v231, 31
	v_writelane_b32 v250, s5, 22
	s_and_b64 s[4:5], s[4:5], exec
	s_cselect_b32 s4, s6, 0x21e00000
	s_mov_b32 s5, 0x20c00000
	s_mov_b32 s6, 0x12a0000
	s_cselect_b32 s5, s5, 0x21400000
	s_cselect_b32 s6, s6, 0x12c0000
	v_writelane_b32 v250, s2, 23
	s_cselect_b32 s7, 0, s2
	s_cselect_b32 s8, 0, 0x400
	s_cselect_b32 s9, s9, 0x16000000
	s_cselect_b32 s10, s10, 0x11a0000
	s_add_u32 s2, s54, s4
	s_addc_u32 s3, s55, 0
	v_writelane_b32 v250, s2, 24
	s_mov_b32 s37, 0
	s_mov_b64 s[30:31], 0x80
	v_writelane_b32 v250, s3, 25
	s_add_u32 s2, s54, s5
	s_addc_u32 s3, s55, 0
	v_writelane_b32 v250, s2, 26
	s_nop 1
	v_writelane_b32 v250, s3, 27
	s_add_u32 s2, s54, s6
	s_addc_u32 s3, s55, 0
	v_writelane_b32 v250, s2, 28
	s_nop 1
	v_writelane_b32 v250, s3, 29
	s_sub_i32 s2, s14, s7
	v_writelane_b32 v250, s2, 30
	s_add_u32 s2, s54, 0x3412000
	s_addc_u32 s3, s55, 0
	s_add_u32 s4, s2, s8
	v_writelane_b32 v250, s2, 31
	s_addc_u32 s5, s3, 0
	s_nop 0
	v_writelane_b32 v250, s3, 32
	v_writelane_b32 v250, s4, 33
	s_add_u32 s2, s54, s9
	s_addc_u32 s3, s55, 0
	v_writelane_b32 v250, s5, 34
	v_writelane_b32 v250, s2, 35
	s_load_dword s5, s[0:1], 0x138
	s_nop 0
	v_writelane_b32 v250, s3, 36
	s_add_u32 s2, s54, s10
	s_addc_u32 s3, s55, 0
	v_writelane_b32 v250, s2, 37
	s_nop 1
	v_writelane_b32 v250, s3, 38
	s_add_u32 s2, s54, 0x14000000
	s_addc_u32 s3, s55, 0
	v_writelane_b32 v250, s2, 39
	s_nop 1
	v_writelane_b32 v250, s3, 40
	s_add_u32 s2, s54, 0x920000
	s_addc_u32 s3, s55, 0
	v_writelane_b32 v250, s2, 41
	s_nop 1
	v_writelane_b32 v250, s3, 42
	s_add_u32 s2, s86, 0x1000
	s_addc_u32 s3, s87, 0
	v_writelane_b32 v250, s2, 43
	s_nop 1
	v_writelane_b32 v250, s3, 44
	s_add_u32 s2, s54, 0x700000
	s_addc_u32 s3, s55, 0
	v_writelane_b32 v250, s2, 45
	s_nop 1
	v_writelane_b32 v250, s3, 46
	s_add_u32 s2, s54, 0x1e000000
	s_addc_u32 s3, s55, 0
	v_writelane_b32 v250, s2, 47
	s_nop 1
	v_writelane_b32 v250, s3, 48
	s_add_u32 s2, s54, 0x900000
	s_addc_u32 s3, s55, 0
	s_add_i32 s4, s18, -1
	v_writelane_b32 v250, s2, 49
	s_cmp_eq_u32 s14, s4
	s_mul_i32 s4, s19, s18
	v_writelane_b32 v250, s3, 50
	s_waitcnt lgkmcnt(0)
	s_mul_i32 s2, s4, s5
	v_writelane_b32 v250, s2, 51
	s_cselect_b64 s[2:3], -1, 0
	v_writelane_b32 v250, s2, 52
	s_nop 1
	v_writelane_b32 v250, s3, 53
	s_add_u32 s2, s54, 0x3412800
	s_addc_u32 s3, s55, 0
	v_writelane_b32 v250, s2, 54
	s_cmpk_lt_i32 s18, 0xc1
	s_nop 0
	v_writelane_b32 v250, s3, 55
	s_cselect_b64 s[2:3], -1, 0
	v_writelane_b32 v250, s2, 56
	s_cmpk_lt_i32 s14, 0x59c
	s_nop 0
	v_writelane_b32 v250, s3, 57
	s_cselect_b64 s[2:3], -1, 0
	v_writelane_b32 v250, s2, 58
	s_nop 1
	v_writelane_b32 v250, s3, 59
	s_add_i32 s2, s14, 0xe0
	v_writelane_b32 v250, s2, 60
	s_add_u32 s2, s54, 0x1de0000
	s_addc_u32 s3, s55, 0
	v_writelane_b32 v250, s2, 61
	s_nop 1
	v_writelane_b32 v250, s3, 62
	s_add_u32 s2, s54, 0x12c0000
	s_addc_u32 s3, s55, 0
	v_writelane_b32 v250, s2, 63
	s_nop 1
	v_writelane_b32 v251, s3, 0
	s_add_u32 s2, s54, 0x12a0000
	s_addc_u32 s3, s55, 0
	v_writelane_b32 v251, s2, 1
	s_nop 1
	v_writelane_b32 v251, s3, 2
	s_add_u32 s2, s54, 0x11a0000
	s_addc_u32 s3, s55, 0
	v_writelane_b32 v251, s2, 3
	s_nop 1
	v_writelane_b32 v251, s3, 4
	s_add_u32 s2, s54, 0x10a0000
	s_addc_u32 s3, s55, 0
	v_writelane_b32 v251, s2, 5
	s_nop 1
	v_writelane_b32 v251, s3, 6
	s_add_u32 s2, s54, 0x2e60000
	s_addc_u32 s3, s55, 0
	v_writelane_b32 v251, s2, 7
	s_nop 1
	v_writelane_b32 v251, s3, 8
	s_add_u32 s2, s78, 0x1600000
	s_addc_u32 s3, s79, 0
	v_writelane_b32 v251, s2, 9
	s_nop 1
	v_writelane_b32 v251, s3, 10
	s_add_u32 s2, s84, 0xb00000
	s_addc_u32 s3, s85, 0
	v_writelane_b32 v251, s2, 11
	s_nop 1
	v_writelane_b32 v251, s3, 12
	s_add_i32 s2, s18, 0xffffff40
	v_writelane_b32 v251, s2, 13
	s_add_i32 s2, s14, 32
	s_add_u32 s33, s54, 0x3b600000
	s_addc_u32 s88, s55, 0
; #define LAS __attribute__((address_space(3)))
; DI unsigned xb_ld(unsigned* p)              { return __hip_atomic_load(p, __ATOMIC_RELAXED, __HIP_MEMORY_SCOPE_AGENT); }
; DI void xcd_barrier_complete(unsigned* bar, unsigned x, unsigned& nloc, unsigned& nx) {
;     const unsigned G = gridDim.x * gridDim.y * gridDim.z;
;     unsigned sum, cnt, mine, sp = 0u;
;     for (;;) {
;         sum = 0u; cnt = 0u; mine = 0u;
; #pragma unroll
;         for (unsigned j = 0; j < 16; ++j) { const unsigned c = xb_ld(&bar[XB_XCNT(j)]); sum += c; cnt += (c > 0u) ? 1u : 0u; mine = (j == x) ? c : mine; }
; __global__ void __launch_bounds__(512, 2) mega(P p, int ph_lo, int ph_hi, unsigned ph_mask) {
;     ...
;     const int G = gridDim.x, c = blockIdx.x;
;     unsigned char* ws = p.ws;
;     volatile LAS unsigned* xbst = (volatile LAS unsigned*)(lds + LDS_BYTES - 16);
;     if (threadIdx.x < 4) xbst[threadIdx.x] = 0u;
;     __syncthreads();
;     const XcdBarrier xbar = xcd_barrier_post((unsigned*)(ws + W_BAR), xbst);
	s_cmpk_lt_i32 s14, 0xc0
	v_writelane_b32 v251, s2, 14
	s_cselect_b64 s[2:3], -1, 0
	v_writelane_b32 v251, s2, 15
	s_nop 1
	v_writelane_b32 v251, s3, 16
	s_add_u32 s2, s54, 0x16000000
	s_addc_u32 s3, s55, 0
	v_writelane_b32 v251, s2, 17
	s_nop 1
	v_writelane_b32 v251, s3, 18
	s_add_u32 s2, s54, 0x38600000
	s_addc_u32 s3, s55, 0
	v_writelane_b32 v251, s2, 19
	s_nop 1
	v_writelane_b32 v251, s3, 20
	s_add_u32 s2, s54, 0x32600000
	s_addc_u32 s3, s55, 0
	v_writelane_b32 v251, s2, 21
	s_nop 1
	v_writelane_b32 v251, s3, 22
	s_add_u32 s2, s54, 0x2c600000
	s_addc_u32 s3, s55, 0
	v_writelane_b32 v251, s2, 23
	s_nop 1
	v_writelane_b32 v251, s3, 24
	s_add_u32 s2, s54, 0x26600000
	s_addc_u32 s3, s55, 0
	v_writelane_b32 v251, s2, 25
	s_nop 1
	v_writelane_b32 v251, s3, 26
	s_add_u32 s2, s54, 0x20600000
	s_addc_u32 s3, s55, 0
	v_writelane_b32 v251, s2, 27
	s_add_i32 s4, s18, s14
	s_nop 0
	v_writelane_b32 v251, s3, 28
	s_add_u32 s2, s54, 0x33e0000
	s_addc_u32 s3, s55, 0
	v_writelane_b32 v251, s2, 29
	s_nop 1
	v_writelane_b32 v251, s3, 30
	s_add_u32 s2, s54, 0x33e2000
	s_addc_u32 s3, s55, 0
	v_writelane_b32 v251, s2, 31
	s_nop 1
	v_writelane_b32 v251, s3, 32
	s_add_u32 s2, s54, 0x20400000
	s_addc_u32 s3, s55, 0
	v_writelane_b32 v251, s2, 33
	s_nop 1
	v_writelane_b32 v251, s3, 34
	s_add_u32 s2, s54, 0x1c000000
	s_addc_u32 s3, s55, 0
	s_add_u32 s42, s54, 0x3402000
	s_addc_u32 s43, s55, 0
	v_writelane_b32 v251, s2, 35
	s_cmpk_lt_i32 s14, 0x200
	s_nop 0
	v_writelane_b32 v251, s3, 36
	s_cselect_b64 s[2:3], -1, 0
	v_writelane_b32 v251, s2, 37
	s_lshl_b32 s8, s18, 1
	s_nop 0
	v_writelane_b32 v251, s3, 38
	s_lshl_b32 s2, s14, 1
	s_cmpk_lt_i32 s14, 0xe0
	v_writelane_b32 v251, s2, 39
	s_cselect_b64 s[2:3], -1, 0
	v_writelane_b32 v251, s2, 40
	s_nop 1
	v_writelane_b32 v251, s3, 41
	s_add_u32 s2, s54, 0x3422800
	s_addc_u32 s3, s55, 0
	v_writelane_b32 v251, s2, 42
	s_cmp_lt_i32 s14, 32
	s_nop 0
	v_writelane_b32 v251, s3, 43
	s_cselect_b64 s[2:3], -1, 0
	v_writelane_b32 v251, s2, 44
	s_cmp_lt_u32 s14, 16
	s_nop 0
	v_writelane_b32 v251, s3, 45
	v_writelane_b32 v251, s24, 46
	s_cselect_b32 s3, s63, s65
	s_cselect_b32 s2, s62, s64
	v_writelane_b32 v251, s25, 47
	v_writelane_b32 v251, s2, 48
	s_nop 1
	v_writelane_b32 v251, s3, 49
	s_cselect_b32 s3, s67, s73
	v_writelane_b32 v251, s72, 50
	s_cselect_b32 s2, s66, s72
	s_lshl_b32 s5, s14, 7
	v_writelane_b32 v251, s73, 51
	v_writelane_b32 v251, s74, 52
	v_writelane_b32 v251, s75, 53
	v_writelane_b32 v251, s76, 54
	v_writelane_b32 v251, s77, 55
	v_writelane_b32 v251, s78, 56
	v_writelane_b32 v251, s79, 57
	v_writelane_b32 v251, s80, 58
	v_writelane_b32 v251, s81, 59
	v_writelane_b32 v251, s82, 60
	v_writelane_b32 v251, s83, 61
	v_writelane_b32 v251, s84, 62
	v_writelane_b32 v252, s86, 0
	v_writelane_b32 v251, s85, 63
	v_writelane_b32 v252, s87, 1
	s_mov_b64 s[84:85], s[60:61]
	s_mov_b64 s[82:83], s[58:59]
	s_mov_b64 s[80:81], s[56:57]
	v_writelane_b32 v252, s80, 2
	s_mov_b32 s66, s20
	s_movk_i32 s56, 0x1200
	v_writelane_b32 v252, s81, 3
	v_writelane_b32 v252, s82, 4
	v_writelane_b32 v252, s83, 5
	v_writelane_b32 v252, s84, 6
	v_writelane_b32 v252, s85, 7
	v_writelane_b32 v252, s86, 8
	v_writelane_b32 v252, s87, 9
	v_writelane_b32 v252, s88, 10
	v_writelane_b32 v252, s89, 11
	v_writelane_b32 v252, s90, 12
	v_writelane_b32 v252, s91, 13
	v_writelane_b32 v252, s92, 14
	v_writelane_b32 v252, s93, 15
	v_writelane_b32 v252, s94, 16
	v_writelane_b32 v252, s95, 17
	v_writelane_b32 v252, s2, 18
	s_load_dwordx16 s[72:87], s[0:1], 0x0
	s_movk_i32 s90, 0xc0
	v_writelane_b32 v252, s3, 19
	s_and_b32 s2, s5, 0x780
	s_add_u32 s68, s54, 0x3423a00
	s_addc_u32 s69, s55, 0
	s_add_u32 s64, s54, 0x3423c00
	s_addc_u32 s65, s55, 0
	s_add_u32 s34, s54, 0x3423d00
	s_addc_u32 s35, s55, 0
	s_add_u32 s24, s54, 0x3423e00
	s_addc_u32 s25, s55, 0
	s_add_u32 s26, s54, 0x3423f00
	s_addc_u32 s27, s55, 0
	s_add_u32 s38, s54, 0x3424000
	s_addc_u32 s39, s55, 0
	s_add_u32 s40, s54, 0x3424100
	s_addc_u32 s41, s55, 0
	s_add_u32 s44, s54, 0x3424200
	s_addc_u32 s45, s55, 0
	s_add_u32 s46, s54, 0x3424300
	s_addc_u32 s47, s55, 0
	s_add_u32 s58, s54, 0x3424400
	s_addc_u32 s59, s55, 0
	s_add_u32 s60, s54, 0x3424500
	s_addc_u32 s61, s55, 0
	s_add_u32 s62, s54, 0x3424600
	s_addc_u32 s63, s55, 0
	s_add_u32 s70, s54, 0x3424700
	s_addc_u32 s71, s55, 0
	s_add_u32 s92, s54, 0x3424800
	s_addc_u32 s93, s55, 0
	s_add_u32 s6, s54, 0x3424900
	s_addc_u32 s7, s55, 0
	s_add_u32 s10, s54, 0x3424a00
	s_addc_u32 s11, s55, 0
	v_writelane_b32 v252, s2, 20
	s_add_u32 s2, s54, 0x3424b00
	s_addc_u32 s3, s55, 0
	v_writelane_b32 v252, s2, 21
	s_cmp_eq_u32 s12, 15
	s_mov_b32 s91, 0xefa18f08
	v_writelane_b32 v252, s3, 22
	s_cselect_b64 s[2:3], -1, 0
	v_writelane_b32 v252, s2, 23
	s_cmp_eq_u32 s12, 14
	s_nop 0
	v_writelane_b32 v252, s3, 24
	s_cselect_b64 s[2:3], -1, 0
	v_writelane_b32 v252, s2, 25
	s_cmp_eq_u32 s12, 13
	s_nop 0
	v_writelane_b32 v252, s3, 26
	s_cselect_b64 s[2:3], -1, 0
	v_writelane_b32 v252, s2, 27
	s_cmp_eq_u32 s12, 12
	s_nop 0
	v_writelane_b32 v252, s3, 28
	s_cselect_b64 s[2:3], -1, 0
	v_writelane_b32 v252, s2, 29
	s_cmp_eq_u32 s12, 11
	s_nop 0
	v_writelane_b32 v252, s3, 30
	s_cselect_b64 s[2:3], -1, 0
	v_writelane_b32 v252, s2, 31
	s_cmp_eq_u32 s12, 10
	s_nop 0
	v_writelane_b32 v252, s3, 32
	s_cselect_b64 s[2:3], -1, 0
	v_writelane_b32 v252, s2, 33
	s_cmp_eq_u32 s12, 9
	s_nop 0
	v_writelane_b32 v252, s3, 34
	s_cselect_b64 s[2:3], -1, 0
	v_writelane_b32 v252, s2, 35
	s_cmp_eq_u32 s12, 8
	s_nop 0
	v_writelane_b32 v252, s3, 36
	s_cselect_b64 s[2:3], -1, 0
	v_writelane_b32 v252, s2, 37
	s_cmp_eq_u32 s12, 7
	s_nop 0
	v_writelane_b32 v252, s3, 38
	s_cselect_b64 s[2:3], -1, 0
; #define LAS __attribute__((address_space(3)))
; DI unsigned xb_ld(unsigned* p)              { return __hip_atomic_load(p, __ATOMIC_RELAXED, __HIP_MEMORY_SCOPE_AGENT); }
; DI unsigned xb_add(unsigned* p, unsigned v) { return __hip_atomic_fetch_add(p, v, __ATOMIC_RELAXED, __HIP_MEMORY_SCOPE_AGENT); }
; DI unsigned xb_xcc_id() { return (unsigned)__builtin_amdgcn_s_getreg((3 << 11) | 20) & 0xFu; }
; DI XcdBarrier xcd_barrier_post(unsigned* bar, volatile LAS unsigned* st) {
;     XcdBarrier b; b.bar = bar; b.x = xb_xcc_id(); b.st = st;
;     if (threadIdx.x == 0) (void)xb_add(&bar[XB_XCNT(b.x)], 1u);
;     return b;
; }
; DI void xcd_barrier_complete(unsigned* bar, unsigned x, unsigned& nloc, unsigned& nx) {
;     const unsigned G = gridDim.x * gridDim.y * gridDim.z;
;     unsigned sum, cnt, mine, sp = 0u;
;     for (;;) {
;         sum = 0u; cnt = 0u; mine = 0u;
; #pragma unroll
;         for (unsigned j = 0; j < 16; ++j) { const unsigned c = xb_ld(&bar[XB_XCNT(j)]); sum += c; cnt += (c > 0u) ? 1u : 0u; mine = (j == x) ? c : mine; }
; __global__ void __launch_bounds__(512, 2) mega(P p, int ph_lo, int ph_hi, unsigned ph_mask) {
;     ...
;                 for (int rp = 0; rp < ((SUBDUP & 8) ? 2 : 1); ++rp) { s5_pass<true>(tid, lds, p, G, (c + G - 192 % G) % G); __syncthreads(); } break;
	v_writelane_b32 v252, s2, 39
	s_cmp_eq_u32 s12, 6
	s_nop 0
	v_writelane_b32 v252, s3, 40
	s_cselect_b64 s[2:3], -1, 0
	v_writelane_b32 v252, s2, 41
	s_cmp_eq_u32 s12, 5
	s_nop 0
	v_writelane_b32 v252, s3, 42
	s_cselect_b64 s[2:3], -1, 0
	v_writelane_b32 v252, s2, 43
	s_cmp_eq_u32 s12, 4
	s_nop 0
	v_writelane_b32 v252, s3, 44
	s_cselect_b64 s[2:3], -1, 0
	v_writelane_b32 v252, s2, 45
	s_cmp_eq_u32 s12, 3
	s_nop 0
	v_writelane_b32 v252, s3, 46
	s_cselect_b64 s[2:3], -1, 0
	v_writelane_b32 v252, s2, 47
	s_cmp_eq_u32 s12, 2
	s_nop 0
	v_writelane_b32 v252, s3, 48
	s_cselect_b64 s[2:3], -1, 0
	v_writelane_b32 v252, s2, 49
	s_cmp_eq_u32 s12, 1
	s_nop 0
	v_writelane_b32 v252, s3, 50
	s_cselect_b64 s[2:3], -1, 0
	v_writelane_b32 v252, s2, 51
	s_cmp_eq_u32 s12, 0
	s_nop 0
	v_writelane_b32 v252, s3, 52
	s_cselect_b64 s[2:3], -1, 0
	v_writelane_b32 v252, s2, 53
	s_lshl_b32 s5, s12, 8
	s_nop 0
	v_writelane_b32 v252, s3, 54
	s_add_u32 s2, s16, s5
	s_addc_u32 s3, s17, 0
	s_mov_b64 s[16:17], s[6:7]
	s_add_u32 s6, s2, 0x1400
	s_addc_u32 s7, s3, 0
	v_writelane_b32 v252, s6, 55
	s_add_u32 s2, s2, 0x2400
	s_addc_u32 s3, s3, 0
	v_writelane_b32 v252, s7, 56
	v_writelane_b32 v252, s2, 57
	s_nop 1
	v_writelane_b32 v252, s3, 58
	s_add_u32 s2, s54, 0x3426c00
	s_addc_u32 s3, s55, 0
	v_writelane_b32 v252, s2, 59
	s_nop 1
	v_writelane_b32 v252, s3, 60
	s_add_u32 s2, s54, 0x3426d00
	s_addc_u32 s3, s55, 0
	v_writelane_b32 v252, s2, 61
	s_nop 1
	v_writelane_b32 v252, s3, 62
	s_add_i32 s2, s14, 0xfffff9a4
	s_cmp_gt_u32 s2, 0xfffffa63
	s_cselect_b64 s[2:3], -1, 0
	v_writelane_b32 v252, s2, 63
	s_nop 1
	v_writelane_b32 v253, s3, 0
	s_abs_i32 s2, s18
	v_cvt_f32_u32_e32 v0, s2
	s_sub_i32 s3, 0, s2
	v_rcp_iflag_f32_e32 v0, v0
	s_nop 0
	v_mul_f32_e32 v0, 0x4f7ffffe, v0
	v_cvt_u32_f32_e32 v0, v0
	s_nop 0
	v_readfirstlane_b32 s5, v0
	s_mul_i32 s3, s3, s5
	s_mul_hi_u32 s3, s5, s3
	s_add_i32 s5, s5, s3
	s_mul_hi_u32 s3, s5, 0xc0
	s_mul_i32 s3, s3, s2
	s_sub_i32 s3, 0xc0, s3
	s_sub_i32 s6, s3, s2
	s_cmp_ge_u32 s3, s2
	s_cselect_b32 s3, s6, s3
	s_sub_i32 s6, s3, s2
	s_cmp_ge_u32 s3, s2
	s_cselect_b32 s3, s6, s3
	s_sub_i32 s3, s4, s3
	s_abs_i32 s4, s3
	s_mul_hi_u32 s5, s4, s5
	s_mul_i32 s5, s5, s2
	s_sub_i32 s4, s4, s5
	s_ashr_i32 s3, s3, 31
	s_sub_i32 s5, s4, s2
	s_cmp_ge_u32 s4, s2
	s_cselect_b32 s4, s5, s4
	s_sub_i32 s5, s4, s2
	s_cmp_ge_u32 s4, s2
	s_cselect_b32 s2, s5, s4
	s_xor_b32 s2, s2, s3
	s_sub_i32 s2, s2, s3
	s_cmpk_lt_i32 s2, 0x200
	v_writelane_b32 v253, s2, 1
	s_cselect_b64 s[2:3], -1, 0
	v_writelane_b32 v253, s2, 2
	v_mbcnt_lo_u32_b32 v0, -1, 0
	s_nop 0
	v_writelane_b32 v253, s3, 3
	s_add_u32 s2, s52, 0x7c00
	s_addc_u32 s3, s53, 0
	v_writelane_b32 v253, s2, 4
	s_ashr_i32 s67, s20, 31
	v_mbcnt_hi_u32_b32 v234, -1, v0
	v_writelane_b32 v253, s3, 5
	s_lshl_b64 s[2:3], s[66:67], 12
	v_writelane_b32 v253, s2, 6
	s_nop 1
	v_writelane_b32 v253, s3, 7
	s_add_u32 s2, s54, 0x4003e00
	s_addc_u32 s3, s55, 0
	v_writelane_b32 v253, s2, 8
	s_ashr_i32 s15, s14, 31
	s_ashr_i32 s19, s18, 31
	v_writelane_b32 v253, s3, 9
	s_lshl_b64 s[2:3], s[66:67], 11
	v_writelane_b32 v253, s2, 10
	s_ashr_i32 s9, s8, 31
	s_mov_b32 s67, s13
	v_writelane_b32 v253, s3, 11
	s_mov_b32 s2, s14
	v_writelane_b32 v253, s2, 12
	s_nop 1
	v_writelane_b32 v253, s3, 13
	s_lshl_b64 s[2:3], s[14:15], 5
	v_writelane_b32 v253, s2, 14
	s_nop 1
	v_writelane_b32 v253, s3, 15
	s_mov_b32 s2, s18
	v_writelane_b32 v253, s2, 16
	s_nop 1
	v_writelane_b32 v253, s3, 17
	s_lshl_b64 s[2:3], s[18:19], 5
	v_writelane_b32 v253, s2, 18
	s_mov_b64 s[18:19], s[10:11]
	s_nop 0
	v_writelane_b32 v253, s3, 19
	s_lshl_b64 s[2:3], s[8:9], 2
	v_writelane_b32 v253, s2, 20
	s_nop 1
	v_writelane_b32 v253, s3, 21
	s_lshl_b64 s[2:3], s[8:9], 14
	v_writelane_b32 v253, s2, 22
	s_nop 1
	v_writelane_b32 v253, s3, 23
	s_mov_b32 s2, s8
	v_writelane_b32 v253, s2, 24
	s_nop 1
	v_writelane_b32 v253, s3, 25
	s_lshl_b64 s[2:3], s[8:9], 13
	v_writelane_b32 v253, s2, 26
	s_nop 1
	v_writelane_b32 v253, s3, 27
	s_add_u32 s2, s54, 0x20603e00
	s_addc_u32 s3, s55, 0
	v_writelane_b32 v253, s2, 28
	s_nop 1
	v_writelane_b32 v253, s3, 29
	s_waitcnt lgkmcnt(0)
; #define LAS __attribute__((address_space(3)))
; __global__ void __launch_bounds__(512, 2) mega(P p, int ph_lo, int ph_hi, unsigned ph_mask) {
;     extern __shared__ __attribute__((aligned(16))) unsigned char lds_raw[];
;     LAS unsigned char* lds = (LAS unsigned char*)lds_raw;
;     cg::grid_group grid = cg::this_grid();
;     const int G = gridDim.x, c = blockIdx.x;
;     unsigned char* ws = p.ws;
;     volatile LAS unsigned* xbst = (volatile LAS unsigned*)(lds + LDS_BYTES - 16);
;     if (threadIdx.x < 4) xbst[threadIdx.x] = 0u;
;     __syncthreads();
;     const XcdBarrier xbar = xcd_barrier_post((unsigned*)(ws + W_BAR), xbst);
;     if (ph_lo > 1000) grid.sync();
; #pragma unroll 1
;     for (int ph2 = ph_lo * 2; ph2 < ph_hi * 2; ++ph2) {
	s_add_u32 s2, s72, 0x7c00
	v_writelane_b32 v253, s72, 30
	s_addc_u32 s3, s73, 0
	s_add_i32 s94, 0, 0x11c00
	v_writelane_b32 v253, s73, 31
	v_writelane_b32 v253, s74, 32
	v_writelane_b32 v253, s75, 33
	v_writelane_b32 v253, s76, 34
	v_writelane_b32 v253, s77, 35
	v_writelane_b32 v253, s78, 36
	v_writelane_b32 v253, s79, 37
	v_writelane_b32 v253, s80, 38
	v_writelane_b32 v253, s81, 39
	v_writelane_b32 v253, s82, 40
	v_writelane_b32 v253, s83, 41
	v_writelane_b32 v253, s84, 42
	v_writelane_b32 v253, s85, 43
	v_writelane_b32 v253, s86, 44
	v_writelane_b32 v253, s87, 45
	v_writelane_b32 v253, s2, 46
	s_load_dwordx16 s[72:87], s[0:1], 0x40
	s_add_i32 s95, 0, 0x14000
	v_writelane_b32 v253, s3, 47
	s_add_i32 s2, 0, 0x1ac00
	v_writelane_b32 v253, s2, 48
	s_add_i32 s2, 0, 0x1ac04
	v_writelane_b32 v253, s2, 49
	s_add_i32 s2, 0, 0x23ff0
	v_writelane_b32 v253, s2, 50
	s_add_i32 s2, 0, 0x23ff4
	v_writelane_b32 v253, s2, 51
	s_waitcnt lgkmcnt(0)
	v_writelane_b32 v253, s72, 52
	s_mov_b32 s3, 0x800000
	s_add_i32 s96, 0, 0x16400
	v_writelane_b32 v254, s84, 0
	v_writelane_b32 v254, s85, 1
	v_writelane_b32 v254, s86, 2
	v_writelane_b32 v254, s87, 3
	v_writelane_b32 v254, s68, 4
	v_writelane_b32 v253, s73, 53
	v_writelane_b32 v253, s74, 54
	v_writelane_b32 v254, s69, 5
	v_writelane_b32 v254, s64, 6
	v_writelane_b32 v253, s75, 55
	v_writelane_b32 v253, s76, 56
	v_writelane_b32 v254, s65, 7
	s_mov_b64 s[64:65], s[34:35]
	v_writelane_b32 v254, s64, 8
	v_writelane_b32 v253, s77, 57
	s_mov_b64 s[76:77], vcc
	v_writelane_b32 v254, s65, 9
	v_writelane_b32 v254, s20, 10
	v_writelane_b32 v253, s78, 58
	v_writelane_b32 v253, s79, 59
	v_writelane_b32 v254, s21, 11
	v_writelane_b32 v254, s22, 12
	v_writelane_b32 v254, s23, 13
	v_writelane_b32 v254, s67, 14
	v_writelane_b32 v254, s66, 15
	v_writelane_b32 v253, s80, 60
	v_writelane_b32 v253, s81, 61
	v_writelane_b32 v254, s67, 16
	v_writelane_b32 v254, s76, 17
	v_writelane_b32 v253, s82, 62
	s_add_i32 s97, 0, 0x18800
	v_writelane_b32 v254, s77, 18
	v_writelane_b32 v254, s42, 19
	s_add_i32 s89, 0, 0x4800
	s_mov_b32 s2, 0x3a800000
	v_writelane_b32 v254, s43, 20
	v_writelane_b32 v254, s24, 21
	v_writelane_b32 v253, s83, 63
	s_movk_i32 s86, 0x110
	v_writelane_b32 v254, s25, 22
	v_writelane_b32 v254, s26, 23
	s_movk_i32 s35, 0x600
	s_nop 0
	v_writelane_b32 v254, s27, 24
	v_writelane_b32 v254, s38, 25
	s_nop 1
	v_writelane_b32 v254, s39, 26
	v_writelane_b32 v254, s40, 27
	s_nop 1
	v_writelane_b32 v254, s41, 28
	v_writelane_b32 v254, s44, 29
	s_nop 1
	v_writelane_b32 v254, s45, 30
	v_writelane_b32 v254, s46, 31
	s_nop 1
	v_writelane_b32 v254, s47, 32
	v_writelane_b32 v254, s58, 33
	s_nop 1
	v_writelane_b32 v254, s59, 34
	v_writelane_b32 v254, s60, 35
	s_nop 1
	v_writelane_b32 v254, s61, 36
	v_writelane_b32 v254, s62, 37
	s_nop 1
	v_writelane_b32 v254, s63, 38
	v_writelane_b32 v254, s70, 39
	s_nop 1
	v_writelane_b32 v254, s71, 40
	v_writelane_b32 v254, s92, 41
	s_nop 1
	v_writelane_b32 v254, s93, 42
	v_writelane_b32 v254, s16, 43
	s_nop 1
	v_writelane_b32 v254, s17, 44
	v_writelane_b32 v254, s18, 45
	s_nop 1
	v_writelane_b32 v254, s19, 46
	v_readfirstlane_b32 s98, v230
	s_lshr_b32 s98, s98, 8
	s_cmp_eq_u32 s98, 1
	s_cbranch_scc0 .Lglobprio_done
	s_setprio 1
.Lglobprio_done:
	s_branch .LBB0_22
.LBB0_19:
	s_or_b64 exec, exec, s[6:7]
	s_waitcnt vmcnt(0)
